# G1: the full vmcnt drain I had put at the item tail removed (older stores only make the next item's counted waits more conservative)
# speedup vs baseline: 1.0104x; 1.0041x over previous
; __device__ __forceinline__ unsigned cvt_pk_bf16(float lo, float hi) { unsigned r; asm volatile("v_cvt_pk_bf16_f32 %0, %1, %2" : "=v"(r) : "v"(lo), "v"(hi)); return r; }
; __device__ __forceinline__ Item decode_item(int it) { Item I; if (it < 1024) { const int b = it >> 8; I.h = (it >> 6) & 3; I.row0 = b * SEQ + (it & 63) * 64; I.L = 64; } else { const int j = it - 1024; I.h = j & 3; I.row0 = MP_ROWS + (j >> 2) * 16; I.L = 16; } I.j = it; return I; }
; __device__ __forceinline__ void gla_g1(const Params& P, unsigned char* lds) {
;     ...
;     for (int it = blockIdx.x; it < NITEM; it += gridDim.x) {
;         const Item I = decode_item(it);
;     ...
;         for (int mt = 0; mt < 8; ++mt)
; #pragma unroll
;             for (int nt = 0; nt < 2; ++nt) { u32x2 w; w.x = cvt_pk_bf16(acc[mt][nt][0], acc[mt][nt][1]); w.y = cvt_pk_bf16(acc[mt][nt][2], acc[mt][nt][3]);
;                 *(u32x2*)(KVT + ((size_t)it * 256 + 32 * wid + 16 * nt + fr) * 128 + 16 * mt + 4 * fq) = w; }
.LBB0_1961:
	s_ashr_i32 s79, s78, 31
	s_lshl_b64 s[16:17], s[78:79], 16
	v_cvt_pk_bf16_f32 v56, v56, v57
	v_cvt_pk_bf16_f32 v57, v58, v59
	v_lshl_add_u64 v[58:59], s[16:17], 0, v[90:91]
	v_lshl_add_u64 v[150:151], v[72:73], 0, v[58:59]
	v_or_b32_e32 v58, 0x1000, v58
	global_store_dwordx2 v[150:151], v[56:57], off
	v_cvt_pk_bf16_f32 v56, v60, v61
	v_lshl_add_u64 v[60:61], v[72:73], 0, v[58:59]
	v_cvt_pk_bf16_f32 v57, v62, v63
	global_store_dwordx2 v[60:61], v[56:57], off
	v_cvt_pk_bf16_f32 v48, v48, v49
	v_cvt_pk_bf16_f32 v49, v50, v51
	v_lshl_add_u64 v[50:51], v[74:75], 0, v[58:59]
	global_store_dwordx2 v[150:151], v[48:49], off offset:32
	v_cvt_pk_bf16_f32 v48, v52, v53
	v_cvt_pk_bf16_f32 v49, v54, v55
	global_store_dwordx2 v[50:51], v[48:49], off
	v_cvt_pk_bf16_f32 v40, v40, v41
	v_cvt_pk_bf16_f32 v41, v42, v43
	v_lshl_add_u64 v[42:43], v[76:77], 0, v[58:59]
	global_store_dwordx2 v[150:151], v[40:41], off offset:64
	v_cvt_pk_bf16_f32 v40, v44, v45
	v_cvt_pk_bf16_f32 v41, v46, v47
	global_store_dwordx2 v[42:43], v[40:41], off
	v_cvt_pk_bf16_f32 v32, v32, v33
	v_cvt_pk_bf16_f32 v33, v34, v35
	v_lshl_add_u64 v[34:35], v[78:79], 0, v[58:59]
	global_store_dwordx2 v[150:151], v[32:33], off offset:96
	v_cvt_pk_bf16_f32 v32, v36, v37
	v_cvt_pk_bf16_f32 v33, v38, v39
	global_store_dwordx2 v[34:35], v[32:33], off
	v_cvt_pk_bf16_f32 v24, v24, v25
	v_cvt_pk_bf16_f32 v25, v26, v27
	v_lshl_add_u64 v[26:27], v[80:81], 0, v[58:59]
	global_store_dwordx2 v[150:151], v[24:25], off offset:128
	v_cvt_pk_bf16_f32 v24, v28, v29
	v_cvt_pk_bf16_f32 v25, v30, v31
	global_store_dwordx2 v[26:27], v[24:25], off
	v_cvt_pk_bf16_f32 v16, v16, v17
	v_cvt_pk_bf16_f32 v17, v18, v19
	v_lshl_add_u64 v[18:19], v[82:83], 0, v[58:59]
	global_store_dwordx2 v[150:151], v[16:17], off offset:160
	v_cvt_pk_bf16_f32 v16, v20, v21
	v_cvt_pk_bf16_f32 v17, v22, v23
	global_store_dwordx2 v[18:19], v[16:17], off
	v_cvt_pk_bf16_f32 v8, v8, v9
	v_cvt_pk_bf16_f32 v9, v10, v11
	v_lshl_add_u64 v[10:11], v[84:85], 0, v[58:59]
	s_cmpk_lg_i32 s58, 0x100
	s_cbranch_scc1 .Lg1map_orig
	s_cmpk_gt_i32 s78, 0x3ff
	s_cbranch_scc1 .Lg1map_end
	s_add_i32 s79, s78, 64
	s_xor_b32 s80, s79, s78
	s_bitcmp1_b32 s80, 8
	s_cbranch_scc0 .Lg1map_set
	s_cmp_lt_u32 s2, 64
	s_cbranch_scc0 .Lg1map_end
	s_and_b32 s79, s2, 7
	s_lshl_b32 s79, s79, 3
	s_lshr_b32 s80, s2, 3
	s_and_b32 s81, s80, 1
	s_lshl_b32 s81, s81, 2
	s_lshr_b32 s80, s80, 1
	s_add_i32 s79, s79, s81
	s_add_i32 s79, s79, s80
	s_addk_i32 s79, 0x400
	s_branch .Lg1map_set
